# residual-add GEMM K-loop: merge-mode check falls through in the non-merge phases (no taken branch per iteration)
# speedup vs baseline: 1.0075x; 1.0075x over previous
; template <class Epi, class Sched, bool ALIGN_EPI = false, bool SP2 = false>
; __device__ __forceinline__ void gemm_phase(PG8_LAS unsigned char* lds, const Gemm g, const Sched& S, const Epi& E, int wave_in) {
;     ...
; #pragma unroll
;         for (int a = 0; a < 2; ++a)
; #pragma unroll
;             for (int b = 0; b < 2; ++b)
; #pragma unroll
;                 for (int m = 0; m < 4; ++m)
; #pragma unroll
;                     for (int n = 0; n < 2; ++n) acc[a][b][m][n] = (f32x4){0.f, 0.f, 0.f, 0.f};
;         cur = nxt; cA = nA; cB = nB; ++ui;
.LBB0_403:
	s_add_u32 s4, s24, 0x80
	s_addc_u32 s5, s25, 0
	s_add_u32 s24, s6, 0x100
	v_mov_b32_e32 v2, 0
	s_addc_u32 s25, s7, 0
	s_mov_b32 s6, 0
	v_mov_b32_e32 v3, v2
	v_mov_b32_e32 v4, v2
	v_mov_b32_e32 v5, v2
	v_mov_b32_e32 v6, v2
	s_waitcnt lgkmcnt(0)
	v_mov_b32_e32 v7, v2
	v_mov_b32_e32 v8, v2
	v_mov_b32_e32 v9, v2
	v_mov_b32_e32 v18, v2
	v_mov_b32_e32 v19, v2
	v_mov_b32_e32 v20, v2
	v_mov_b32_e32 v21, v2
	v_mov_b32_e32 v22, v2
	v_mov_b32_e32 v23, v2
	s_waitcnt vmcnt(0)
	v_mov_b32_e32 v24, v2
	v_mov_b32_e32 v25, v2
	v_mov_b32_e32 v34, v2
	v_mov_b32_e32 v35, v2
	v_mov_b32_e32 v36, v2
	v_mov_b32_e32 v37, v2
	v_mov_b32_e32 v38, v2
	v_mov_b32_e32 v39, v2
	v_mov_b32_e32 v40, v2
	v_mov_b32_e32 v41, v2
	v_mov_b32_e32 v50, v2
	v_mov_b32_e32 v51, v2
	v_mov_b32_e32 v52, v2
	v_mov_b32_e32 v53, v2
	v_mov_b32_e32 v54, v2
	v_mov_b32_e32 v55, v2
	v_mov_b32_e32 v56, v2
	v_mov_b32_e32 v57, v2
	v_mov_b32_e32 v10, v2
	v_mov_b32_e32 v11, v2
	v_mov_b32_e32 v12, v2
	v_mov_b32_e32 v13, v2
	v_mov_b32_e32 v14, v2
	v_mov_b32_e32 v15, v2
	v_mov_b32_e32 v16, v2
	v_mov_b32_e32 v17, v2
	v_mov_b32_e32 v26, v2
	v_mov_b32_e32 v27, v2
	v_mov_b32_e32 v28, v2
	v_mov_b32_e32 v29, v2
	v_mov_b32_e32 v30, v2
	v_mov_b32_e32 v31, v2
	v_mov_b32_e32 v32, v2
	v_mov_b32_e32 v33, v2
	v_mov_b32_e32 v42, v2
	v_mov_b32_e32 v43, v2
	v_mov_b32_e32 v44, v2
	v_mov_b32_e32 v45, v2
	v_mov_b32_e32 v46, v2
	v_mov_b32_e32 v47, v2
	v_mov_b32_e32 v48, v2
	v_mov_b32_e32 v49, v2
	v_mov_b32_e32 v58, v2
	v_mov_b32_e32 v59, v2
	v_mov_b32_e32 v60, v2
	v_mov_b32_e32 v61, v2
	v_mov_b32_e32 v62, v2
	v_mov_b32_e32 v63, v2
	v_mov_b32_e32 v64, v2
	v_mov_b32_e32 v65, v2
	v_mov_b32_e32 v66, v2
	v_mov_b32_e32 v67, v2
	v_mov_b32_e32 v68, v2
	v_mov_b32_e32 v69, v2
	v_mov_b32_e32 v70, v2
	v_mov_b32_e32 v71, v2
	v_mov_b32_e32 v72, v2
	v_mov_b32_e32 v73, v2
	v_mov_b32_e32 v82, v2
	v_mov_b32_e32 v83, v2
	v_mov_b32_e32 v84, v2
	v_mov_b32_e32 v85, v2
	v_mov_b32_e32 v86, v2
	v_mov_b32_e32 v87, v2
	v_mov_b32_e32 v88, v2
	v_mov_b32_e32 v89, v2
	v_mov_b32_e32 v98, v2
	v_mov_b32_e32 v99, v2
	v_mov_b32_e32 v100, v2
	v_mov_b32_e32 v101, v2
	v_mov_b32_e32 v102, v2
	v_mov_b32_e32 v103, v2
	v_mov_b32_e32 v104, v2
	v_mov_b32_e32 v105, v2
	v_mov_b32_e32 v114, v2
	v_mov_b32_e32 v115, v2
	v_mov_b32_e32 v116, v2
	v_mov_b32_e32 v117, v2
	v_mov_b32_e32 v118, v2
	v_mov_b32_e32 v119, v2
	v_mov_b32_e32 v120, v2
	v_mov_b32_e32 v121, v2
	v_mov_b32_e32 v74, v2
	v_mov_b32_e32 v75, v2
	v_mov_b32_e32 v76, v2
	v_mov_b32_e32 v77, v2
	v_mov_b32_e32 v78, v2
	v_mov_b32_e32 v79, v2
	v_mov_b32_e32 v80, v2
	v_mov_b32_e32 v81, v2
	v_mov_b32_e32 v90, v2
	v_mov_b32_e32 v91, v2
	v_mov_b32_e32 v92, v2
	v_mov_b32_e32 v93, v2
	v_mov_b32_e32 v94, v2
	v_mov_b32_e32 v95, v2
	v_mov_b32_e32 v96, v2
	v_mov_b32_e32 v97, v2
	v_mov_b32_e32 v106, v2
	v_mov_b32_e32 v107, v2
	v_mov_b32_e32 v108, v2
	v_mov_b32_e32 v109, v2
	v_mov_b32_e32 v110, v2
	v_mov_b32_e32 v111, v2
	v_mov_b32_e32 v112, v2
	v_mov_b32_e32 v113, v2
	v_mov_b32_e32 v122, v2
	v_mov_b32_e32 v123, v2
	v_mov_b32_e32 v124, v2
	v_mov_b32_e32 v125, v2
	v_mov_b32_e32 v126, v2
	v_mov_b32_e32 v127, v2
	v_mov_b32_e32 v128, v2
	v_mov_b32_e32 v129, v2
	s_nop 0
	s_nop 0
	s_nop 0
	s_nop 0
	s_nop 0
.LBB0_404:
	s_cmp_eq_u32 s100, 1
	s_cbranch_scc1 .Lmg_check

; template <class Epi, class Sched, bool ALIGN_EPI = false, bool SP2 = false>
; __device__ __forceinline__ void gemm_phase(PG8_LAS unsigned char* lds, const Gemm g, const Sched& S, const Epi& E, int wave_in) {
;     ...
;         for (int t = 0; t < nt; t += 2) {
;             const bool last = (t == nt - 2);
;             const char* a1 = cA + (size_t)(t + 1) * kstep;
;             const char* a2 = last ? nA : cA + (size_t)(t + 2) * kstep; const char* b2 = last ? nB : cB + (size_t)(t + 2) * kstep;
;             const char* a3 = a2 + kstep; const char* b3 = b2 + kstep;
;             if (last && has_next) S.a_ready(nxt);
.Lmg_check:
	s_cmp_eq_u32 s6, 16
	s_cbranch_scc1 .Lmg_rescale01
	s_cmp_eq_u32 s6, 24
	s_cbranch_scc1 .Lmg_rescale12
	s_branch .Lmg_nohook
